# grid barrier arrival-time L1 invalidate only (no flat release)
# speedup vs baseline: 1.0027x; 1.0027x over previous
; __device__ __forceinline__ unsigned xb_ld(unsigned* p)              { return __hip_atomic_load(p, __ATOMIC_RELAXED, __HIP_MEMORY_SCOPE_AGENT); }
; __device__ __forceinline__ unsigned xb_add(unsigned* p, unsigned v) { return __hip_atomic_fetch_add(p, v, __ATOMIC_RELAXED, __HIP_MEMORY_SCOPE_AGENT); }
; #define XB_SPIN(cond, bar) do { unsigned _sp = 0; while (cond) { __builtin_amdgcn_s_sleep(1); \
;     if ((++_sp & 255u) == 0u) { if (xb_ld(&(bar)[XB_TMO])) break; if (_sp > XB_SPIN_CAP) { atomicAdd(&(bar)[XB_TMO], 1u); break; } } } } while (0)
; __device__ __forceinline__ void xcd_barrier(const XcdBarrier& b, int xtid) {
;     ...
;             if (og + 1u == (tg + 1u) * nx) xb_add(&bar[XB_TOPGEN], 1u);
;             else XB_SPIN(xb_ld(&bar[XB_TOPGEN]) == tg, bar);
;             __builtin_amdgcn_fence(__ATOMIC_ACQUIRE, "agent");
;             xb_add(&bar[XB_XGEN(b.x)], 1u);
;             asm volatile("s_waitcnt vmcnt(0)" ::: "memory");
.LBB0_154:
	s_or_b64 exec, exec, s[6:7]
	s_mov_b64 s[6:7], exec
	v_mbcnt_lo_u32_b32 v0, s6, 0
	v_mbcnt_hi_u32_b32 v0, s7, v0
	v_cmp_eq_u32_e32 vcc, 0, v0
	s_waitcnt vmcnt(0)
	s_nop 0
	s_and_saveexec_b64 s[8:9], vcc
	s_cbranch_execz .LBB0_156
	s_bcnt1_i32_b64 s6, s[6:7]
	v_mov_b32_e32 v0, s6
	global_atomic_add v201, v0, s[4:5] offset:1024

; __device__ __forceinline__ unsigned xb_ld(unsigned* p)              { return __hip_atomic_load(p, __ATOMIC_RELAXED, __HIP_MEMORY_SCOPE_AGENT); }
; __device__ __forceinline__ unsigned xb_add(unsigned* p, unsigned v) { return __hip_atomic_fetch_add(p, v, __ATOMIC_RELAXED, __HIP_MEMORY_SCOPE_AGENT); }
; #define XB_SPIN(cond, bar) do { unsigned _sp = 0; while (cond) { __builtin_amdgcn_s_sleep(1); \
;     if ((++_sp & 255u) == 0u) { if (xb_ld(&(bar)[XB_TMO])) break; if (_sp > XB_SPIN_CAP) { atomicAdd(&(bar)[XB_TMO], 1u); break; } } } } while (0)
; __device__ __forceinline__ void xcd_barrier(const XcdBarrier& b, int xtid) {
;     ...
;             if (og + 1u == (tg + 1u) * nx) xb_add(&bar[XB_TOPGEN], 1u);
;             else XB_SPIN(xb_ld(&bar[XB_TOPGEN]) == tg, bar);
;             __builtin_amdgcn_fence(__ATOMIC_ACQUIRE, "agent");
;             xb_add(&bar[XB_XGEN(b.x)], 1u);
;             asm volatile("s_waitcnt vmcnt(0)" ::: "memory");
.LBB0_272:
	s_or_b64 exec, exec, s[8:9]
	s_mov_b64 s[8:9], exec
	v_mbcnt_lo_u32_b32 v0, s8, 0
	v_mbcnt_hi_u32_b32 v0, s9, v0
	v_cmp_eq_u32_e32 vcc, 0, v0
	s_waitcnt vmcnt(0)
	s_nop 0
	s_and_saveexec_b64 s[10:11], vcc
	s_cbranch_execz .LBB0_274
	s_bcnt1_i32_b64 s8, s[8:9]
	v_mov_b32_e32 v0, s8
	global_atomic_add v201, v0, s[6:7] offset:1024

; __device__ __forceinline__ unsigned xb_ld(unsigned* p)              { return __hip_atomic_load(p, __ATOMIC_RELAXED, __HIP_MEMORY_SCOPE_AGENT); }
; __device__ __forceinline__ unsigned xb_add(unsigned* p, unsigned v) { return __hip_atomic_fetch_add(p, v, __ATOMIC_RELAXED, __HIP_MEMORY_SCOPE_AGENT); }
; #define XB_SPIN(cond, bar) do { unsigned _sp = 0; while (cond) { __builtin_amdgcn_s_sleep(1); \
;     if ((++_sp & 255u) == 0u) { if (xb_ld(&(bar)[XB_TMO])) break; if (_sp > XB_SPIN_CAP) { atomicAdd(&(bar)[XB_TMO], 1u); break; } } } } while (0)
; __device__ __forceinline__ void xcd_barrier(const XcdBarrier& b, int xtid) {
;     ...
;             if (og + 1u == (tg + 1u) * nx) xb_add(&bar[XB_TOPGEN], 1u);
;             else XB_SPIN(xb_ld(&bar[XB_TOPGEN]) == tg, bar);
;             __builtin_amdgcn_fence(__ATOMIC_ACQUIRE, "agent");
;             xb_add(&bar[XB_XGEN(b.x)], 1u);
;             asm volatile("s_waitcnt vmcnt(0)" ::: "memory");
.LBB0_475:
	s_or_b64 exec, exec, s[10:11]
	s_mov_b64 s[10:11], exec
	v_mbcnt_lo_u32_b32 v0, s10, 0
	v_mbcnt_hi_u32_b32 v0, s11, v0
	v_cmp_eq_u32_e32 vcc, 0, v0
	s_waitcnt vmcnt(0)
	s_nop 0
	s_and_saveexec_b64 s[12:13], vcc
	s_cbranch_execz .LBB0_477
	s_bcnt1_i32_b64 s10, s[10:11]
	v_mov_b32_e32 v0, s10
	global_atomic_add v201, v0, s[8:9] offset:1024

; __device__ __forceinline__ unsigned xb_ld(unsigned* p)              { return __hip_atomic_load(p, __ATOMIC_RELAXED, __HIP_MEMORY_SCOPE_AGENT); }
; __device__ __forceinline__ unsigned xb_add(unsigned* p, unsigned v) { return __hip_atomic_fetch_add(p, v, __ATOMIC_RELAXED, __HIP_MEMORY_SCOPE_AGENT); }
; #define XB_SPIN(cond, bar) do { unsigned _sp = 0; while (cond) { __builtin_amdgcn_s_sleep(1); \
;     if ((++_sp & 255u) == 0u) { if (xb_ld(&(bar)[XB_TMO])) break; if (_sp > XB_SPIN_CAP) { atomicAdd(&(bar)[XB_TMO], 1u); break; } } } } while (0)
; __device__ __forceinline__ void xcd_barrier(const XcdBarrier& b, int xtid) {
;     ...
;             if (og + 1u == (tg + 1u) * nx) xb_add(&bar[XB_TOPGEN], 1u);
;             else XB_SPIN(xb_ld(&bar[XB_TOPGEN]) == tg, bar);
;             __builtin_amdgcn_fence(__ATOMIC_ACQUIRE, "agent");
;             xb_add(&bar[XB_XGEN(b.x)], 1u);
;             asm volatile("s_waitcnt vmcnt(0)" ::: "memory");
.LBB0_541:
	s_or_b64 exec, exec, s[12:13]
	s_mov_b64 s[12:13], exec
	v_mbcnt_lo_u32_b32 v0, s12, 0
	v_mbcnt_hi_u32_b32 v0, s13, v0
	v_cmp_eq_u32_e32 vcc, 0, v0
	s_waitcnt vmcnt(0)
	s_nop 0
	s_and_saveexec_b64 s[14:15], vcc
	s_cbranch_execz .LBB0_543
	s_bcnt1_i32_b64 s12, s[12:13]
	v_mov_b32_e32 v0, s12
	global_atomic_add v201, v0, s[8:9] offset:1024
